# pool mixer row loop rewritten: all 16 window loads issued together under their lane masks (one wait) instead of 17 serialized load-wait round trips; same summation order
# speedup vs baseline: 1.0106x; 1.0106x over previous
; __device__ __forceinline__ unsigned cvt_pk_bf16(float lo, float hi) { unsigned r; asm volatile("v_cvt_pk_bf16_f32 %0, %1, %2" : "=v"(r) : "v"(lo), "v"(hi)); return r; }
; __device__ __forceinline__ float bf_lo(unsigned w) { return __uint_as_float(w << 16); }
; __device__ __forceinline__ float bf_hi(unsigned w) { return __uint_as_float(w & 0xffff0000u); }
; __device__ __forceinline__ void pool_phase(const bf16_t* ZP, bf16_t* CAT, int gw, int NGW, int lane) {
;     const int gi = lane >> 4, w = 2 << gi, lo = w >> 1, hi = w - 1 - lo;
;     for (int row = gw; row < MTOK; row += NGW) {
;         const int tl = row & (SEQL - 1); float acc[8];
; #pragma unroll
;         for (int j = 0; j < 8; ++j) acc[j] = 0.f;
;         const int d0 = -min(lo, tl), d1 = min(hi, SEQL - 1 - tl);
; #pragma unroll
;         for (int d = -8; d <= 7; ++d) if (d >= d0 && d <= d1) { const u32x4 z = *(const u32x4*)(ZP + (size_t)(row + d) * 512 + lane * 8);
;             acc[0] += bf_lo(z.x); acc[1] += bf_hi(z.x); acc[2] += bf_lo(z.y); acc[3] += bf_hi(z.y); acc[4] += bf_lo(z.z); acc[5] += bf_hi(z.z); acc[6] += bf_lo(z.w); acc[7] += bf_hi(z.w); }
;         const float inv = 1.0f / (float)(d1 - d0 + 1); const u32x4 z = *(const u32x4*)(ZP + (size_t)row * 512 + lane * 8);
;         u32x4 o; o.x = cvt_pk_bf16(acc[0] * inv - bf_lo(z.x), acc[1] * inv - bf_hi(z.x)); o.y = cvt_pk_bf16(acc[2] * inv - bf_lo(z.y), acc[3] * inv - bf_hi(z.y));
;         o.z = cvt_pk_bf16(acc[4] * inv - bf_lo(z.z), acc[5] * inv - bf_hi(z.z)); o.w = cvt_pk_bf16(acc[6] * inv - bf_lo(z.w), acc[7] * inv - bf_hi(z.w));
;         *(u32x4*)(CAT + (size_t)row * 1024 + lane * 8) = o;
;     }
.LBB0_739:
	s_or_b64 exec, exec, s[0:1]
	v_add3_u32 v0, v0, v16, 1
	v_cvt_f32_i32_e32 v0, v0
	s_add_i32 s8, s8, s38
	s_cmp_lt_i32 s8, 0x10000
	v_div_scale_f32 v16, s[0:1], v0, v0, 1.0
	v_rcp_f32_e32 v17, v16
	v_div_scale_f32 v24, vcc, 1.0, v0, 1.0
	v_readlane_b32 s0, v254, 55
	v_fma_f32 v25, -v16, v17, 1.0
	v_fmac_f32_e32 v17, v25, v17
	v_mul_f32_e32 v25, v24, v17
	v_fma_f32 v26, -v16, v25, v24
	v_fmac_f32_e32 v25, v26, v17
	v_fma_f32 v16, -v16, v25, v24
	v_div_fmas_f32 v16, v16, v17, v25
	v_div_fixup_f32 v0, v16, v0, 1.0
	v_readlane_b32 s1, v254, 56
	s_waitcnt vmcnt(0)
	v_lshlrev_b32_e32 v16, 16, v162
	v_and_b32_e32 v17, 0xffff0000, v162
	v_lshlrev_b32_e32 v20, 16, v163
	v_and_b32_e32 v21, 0xffff0000, v163
	v_lshlrev_b32_e32 v24, 16, v164
	v_and_b32_e32 v22, 0xffff0000, v164
	v_lshlrev_b32_e32 v25, 16, v165
	v_and_b32_e32 v23, 0xffff0000, v165
	v_fma_f32 v8, v0, v8, -v16
	v_fma_f32 v9, v0, v9, -v17
	v_fma_f32 v10, v0, v10, -v20
	v_fma_f32 v11, v0, v11, -v21
	v_fma_f32 v12, v0, v12, -v24
	v_fma_f32 v13, v0, v13, -v22
	v_fma_f32 v14, v0, v14, -v25
	v_fma_f32 v0, v0, v15, -v23
	v_cvt_pk_bf16_f32 v8, v8, v9
	v_cvt_pk_bf16_f32 v9, v10, v11
	v_cvt_pk_bf16_f32 v10, v12, v13
	v_cvt_pk_bf16_f32 v11, v14, v0
	global_store_dwordx4 v[4:5], v[8:11], off
	v_lshl_add_u64 v[4:5], v[4:5], 0, s[0:1]
	v_readlane_b32 s0, v254, 57
	v_readlane_b32 s1, v254, 58
	s_nop 1
	v_lshl_add_u64 v[6:7], v[6:7], 0, s[0:1]
	s_cbranch_scc0 .LBB0_772
.LBB0_740:
	s_and_b32 s9, s8, 0x1fff
	v_min_i32_e32 v0, s9, v18
	s_xor_b32 s0, s9, 0x1fff
	v_min_i32_e32 v16, s0, v19
	v_mov_b64_e32 v[130:131], 0
	v_mov_b64_e32 v[132:133], 0
	v_mov_b64_e32 v[134:135], 0
	v_mov_b64_e32 v[136:137], 0
	v_mov_b64_e32 v[138:139], 0
	v_mov_b64_e32 v[140:141], 0
	v_mov_b64_e32 v[142:143], 0
	v_mov_b64_e32 v[144:145], 0
	v_mov_b64_e32 v[146:147], 0
	v_mov_b64_e32 v[148:149], 0
	v_mov_b64_e32 v[150:151], 0
	v_mov_b64_e32 v[152:153], 0
	v_mov_b64_e32 v[154:155], 0
	v_mov_b64_e32 v[156:157], 0
	v_mov_b64_e32 v[158:159], 0
	v_mov_b64_e32 v[160:161], 0
	v_mov_b64_e32 v[162:163], 0
	v_mov_b64_e32 v[164:165], 0
	v_mov_b64_e32 v[166:167], 0
	v_mov_b64_e32 v[168:169], 0
	v_mov_b64_e32 v[170:171], 0
	v_mov_b64_e32 v[172:173], 0
	v_mov_b64_e32 v[174:175], 0
	v_mov_b64_e32 v[176:177], 0
	v_mov_b64_e32 v[178:179], 0
	v_mov_b64_e32 v[180:181], 0
	v_mov_b64_e32 v[182:183], 0
	v_mov_b64_e32 v[184:185], 0
	v_mov_b64_e32 v[186:187], 0
	v_mov_b64_e32 v[188:189], 0
	v_mov_b64_e32 v[190:191], 0
	v_mov_b64_e32 v[192:193], 0
	v_add_co_u32_e32 v196, vcc, 0xffffe000, v6
	s_nop 1
	v_addc_co_u32_e32 v197, vcc, -1, v7, vcc
	v_add_co_u32_e32 v198, vcc, 0xfffff000, v6
	s_nop 1
	v_addc_co_u32_e32 v199, vcc, -1, v7, vcc
	v_add_co_u32_e32 v200, vcc, 0x1000, v6
	s_nop 1
	v_addc_co_u32_e32 v201, vcc, 0, v7, vcc
	s_mov_b64 s[0:1], exec
	v_cmp_lt_u32_e32 vcc, 7, v0
	s_and_b64 exec, s[0:1], vcc
	global_load_dwordx4 v[130:133], v[196:197], off
	s_mov_b64 exec, s[0:1]
	v_cmp_lt_u32_e32 vcc, 6, v0
	s_and_b64 exec, s[0:1], vcc
	global_load_dwordx4 v[134:137], v[196:197], off offset:1024
	s_mov_b64 exec, s[0:1]
	v_cmp_lt_u32_e32 vcc, 5, v0
	s_and_b64 exec, s[0:1], vcc
	global_load_dwordx4 v[138:141], v[196:197], off offset:2048
	s_mov_b64 exec, s[0:1]
	v_cmp_lt_u32_e32 vcc, 4, v0
	s_and_b64 exec, s[0:1], vcc
	global_load_dwordx4 v[142:145], v[196:197], off offset:3072
	s_mov_b64 exec, s[0:1]
	v_cmp_lt_u32_e32 vcc, 3, v0
	s_and_b64 exec, s[0:1], vcc
	global_load_dwordx4 v[146:149], v[198:199], off
	s_mov_b64 exec, s[0:1]
	v_cmp_lt_u32_e32 vcc, 2, v0
	s_and_b64 exec, s[0:1], vcc
	global_load_dwordx4 v[150:153], v[198:199], off offset:1024
	s_mov_b64 exec, s[0:1]
	v_cmp_lt_u32_e32 vcc, 1, v0
	s_and_b64 exec, s[0:1], vcc
	global_load_dwordx4 v[154:157], v[198:199], off offset:2048
	s_mov_b64 exec, s[0:1]
	v_cmp_lt_u32_e32 vcc, 0, v0
	s_and_b64 exec, s[0:1], vcc
	global_load_dwordx4 v[158:161], v[198:199], off offset:3072
	s_mov_b64 exec, s[0:1]
	global_load_dwordx4 v[162:165], v[6:7], off
	v_cmp_le_i32_e32 vcc, 1, v16
	s_and_b64 exec, s[0:1], vcc
	global_load_dwordx4 v[166:169], v[6:7], off offset:1024
	s_mov_b64 exec, s[0:1]
	v_cmp_le_i32_e32 vcc, 2, v16
	s_and_b64 exec, s[0:1], vcc
	global_load_dwordx4 v[170:173], v[6:7], off offset:2048
	s_mov_b64 exec, s[0:1]
	v_cmp_le_i32_e32 vcc, 3, v16
	s_and_b64 exec, s[0:1], vcc
	global_load_dwordx4 v[174:177], v[6:7], off offset:3072
	s_mov_b64 exec, s[0:1]
	v_cmp_le_i32_e32 vcc, 4, v16
	s_and_b64 exec, s[0:1], vcc
	global_load_dwordx4 v[178:181], v[200:201], off
	s_mov_b64 exec, s[0:1]
	v_cmp_le_i32_e32 vcc, 5, v16
	s_and_b64 exec, s[0:1], vcc
	global_load_dwordx4 v[182:185], v[200:201], off offset:1024
	s_mov_b64 exec, s[0:1]
	v_cmp_le_i32_e32 vcc, 6, v16
	s_and_b64 exec, s[0:1], vcc
	global_load_dwordx4 v[186:189], v[200:201], off offset:2048
	s_mov_b64 exec, s[0:1]
	v_cmp_le_i32_e32 vcc, 7, v16
	s_and_b64 exec, s[0:1], vcc
	global_load_dwordx4 v[190:193], v[200:201], off offset:3072
	s_mov_b64 exec, s[0:1]
	s_waitcnt vmcnt(0)
; __device__ __forceinline__ float bf_lo(unsigned w) { return __uint_as_float(w << 16); }
; __device__ __forceinline__ float bf_hi(unsigned w) { return __uint_as_float(w & 0xffff0000u); }
; __device__ __forceinline__ void pool_phase(const bf16_t* ZP, bf16_t* CAT, int gw, int NGW, int lane) {
;     ...
;         for (int d = -8; d <= 7; ++d) if (d >= d0 && d <= d1) { const u32x4 z = *(const u32x4*)(ZP + (size_t)(row + d) * 512 + lane * 8);
;             acc[0] += bf_lo(z.x); acc[1] += bf_hi(z.x); acc[2] += bf_lo(z.y); acc[3] += bf_hi(z.y); acc[4] += bf_lo(z.z); acc[5] += bf_hi(z.z); acc[6] += bf_lo(z.w); acc[7] += bf_hi(z.w); }
	v_lshlrev_b32_e32 v20, 16, v130
	v_and_b32_e32 v21, 0xffff0000, v130
	v_lshlrev_b32_e32 v22, 16, v131
	v_and_b32_e32 v23, 0xffff0000, v131
	v_lshlrev_b32_e32 v24, 16, v132
	v_and_b32_e32 v25, 0xffff0000, v132
	v_lshlrev_b32_e32 v194, 16, v133
	v_and_b32_e32 v195, 0xffff0000, v133
	v_pk_add_f32 v[8:9], v[20:21], 0 op_sel_hi:[1,0]
	v_pk_add_f32 v[10:11], v[22:23], 0 op_sel_hi:[1,0]
	v_pk_add_f32 v[12:13], v[24:25], 0 op_sel_hi:[1,0]
	v_pk_add_f32 v[14:15], v[194:195], 0 op_sel_hi:[1,0]
	v_lshlrev_b32_e32 v20, 16, v134
	v_and_b32_e32 v21, 0xffff0000, v134
	v_lshlrev_b32_e32 v22, 16, v135
	v_and_b32_e32 v23, 0xffff0000, v135
	v_lshlrev_b32_e32 v24, 16, v136
	v_and_b32_e32 v25, 0xffff0000, v136
	v_lshlrev_b32_e32 v194, 16, v137
	v_and_b32_e32 v195, 0xffff0000, v137
	v_pk_add_f32 v[8:9], v[8:9], v[20:21]
	v_pk_add_f32 v[10:11], v[10:11], v[22:23]
	v_pk_add_f32 v[12:13], v[12:13], v[24:25]
	v_pk_add_f32 v[14:15], v[14:15], v[194:195]
	v_lshlrev_b32_e32 v20, 16, v138
	v_and_b32_e32 v21, 0xffff0000, v138
	v_lshlrev_b32_e32 v22, 16, v139
	v_and_b32_e32 v23, 0xffff0000, v139
	v_lshlrev_b32_e32 v24, 16, v140
	v_and_b32_e32 v25, 0xffff0000, v140
	v_lshlrev_b32_e32 v194, 16, v141
	v_and_b32_e32 v195, 0xffff0000, v141
	v_pk_add_f32 v[8:9], v[8:9], v[20:21]
	v_pk_add_f32 v[10:11], v[10:11], v[22:23]
	v_pk_add_f32 v[12:13], v[12:13], v[24:25]
	v_pk_add_f32 v[14:15], v[14:15], v[194:195]
	v_lshlrev_b32_e32 v20, 16, v142
	v_and_b32_e32 v21, 0xffff0000, v142
	v_lshlrev_b32_e32 v22, 16, v143
	v_and_b32_e32 v23, 0xffff0000, v143
	v_lshlrev_b32_e32 v24, 16, v144
	v_and_b32_e32 v25, 0xffff0000, v144
	v_lshlrev_b32_e32 v194, 16, v145
	v_and_b32_e32 v195, 0xffff0000, v145
	v_pk_add_f32 v[8:9], v[8:9], v[20:21]
	v_pk_add_f32 v[10:11], v[10:11], v[22:23]
	v_pk_add_f32 v[12:13], v[12:13], v[24:25]
	v_pk_add_f32 v[14:15], v[14:15], v[194:195]
	v_lshlrev_b32_e32 v20, 16, v146
	v_and_b32_e32 v21, 0xffff0000, v146
	v_lshlrev_b32_e32 v22, 16, v147
	v_and_b32_e32 v23, 0xffff0000, v147
	v_lshlrev_b32_e32 v24, 16, v148
	v_and_b32_e32 v25, 0xffff0000, v148
	v_lshlrev_b32_e32 v194, 16, v149
	v_and_b32_e32 v195, 0xffff0000, v149
	v_pk_add_f32 v[8:9], v[8:9], v[20:21]
	v_pk_add_f32 v[10:11], v[10:11], v[22:23]
	v_pk_add_f32 v[12:13], v[12:13], v[24:25]
	v_pk_add_f32 v[14:15], v[14:15], v[194:195]
	v_lshlrev_b32_e32 v20, 16, v150
	v_and_b32_e32 v21, 0xffff0000, v150
	v_lshlrev_b32_e32 v22, 16, v151
	v_and_b32_e32 v23, 0xffff0000, v151
	v_lshlrev_b32_e32 v24, 16, v152
	v_and_b32_e32 v25, 0xffff0000, v152
	v_lshlrev_b32_e32 v194, 16, v153
	v_and_b32_e32 v195, 0xffff0000, v153
	v_pk_add_f32 v[8:9], v[8:9], v[20:21]
	v_pk_add_f32 v[10:11], v[10:11], v[22:23]
	v_pk_add_f32 v[12:13], v[12:13], v[24:25]
	v_pk_add_f32 v[14:15], v[14:15], v[194:195]
	v_lshlrev_b32_e32 v20, 16, v154
	v_and_b32_e32 v21, 0xffff0000, v154
	v_lshlrev_b32_e32 v22, 16, v155
	v_and_b32_e32 v23, 0xffff0000, v155
	v_lshlrev_b32_e32 v24, 16, v156
	v_and_b32_e32 v25, 0xffff0000, v156
	v_lshlrev_b32_e32 v194, 16, v157
	v_and_b32_e32 v195, 0xffff0000, v157
	v_pk_add_f32 v[8:9], v[8:9], v[20:21]
	v_pk_add_f32 v[10:11], v[10:11], v[22:23]
	v_pk_add_f32 v[12:13], v[12:13], v[24:25]
	v_pk_add_f32 v[14:15], v[14:15], v[194:195]
	v_lshlrev_b32_e32 v20, 16, v158
	v_and_b32_e32 v21, 0xffff0000, v158
	v_lshlrev_b32_e32 v22, 16, v159
	v_and_b32_e32 v23, 0xffff0000, v159
	v_lshlrev_b32_e32 v24, 16, v160
	v_and_b32_e32 v25, 0xffff0000, v160
	v_lshlrev_b32_e32 v194, 16, v161
	v_and_b32_e32 v195, 0xffff0000, v161
	v_pk_add_f32 v[8:9], v[8:9], v[20:21]
	v_pk_add_f32 v[10:11], v[10:11], v[22:23]
	v_pk_add_f32 v[12:13], v[12:13], v[24:25]
	v_pk_add_f32 v[14:15], v[14:15], v[194:195]
; __device__ __forceinline__ float bf_lo(unsigned w) { return __uint_as_float(w << 16); }
; __device__ __forceinline__ float bf_hi(unsigned w) { return __uint_as_float(w & 0xffff0000u); }
; __device__ __forceinline__ void pool_phase(const bf16_t* ZP, bf16_t* CAT, int gw, int NGW, int lane) {
;     ...
;         for (int d = -8; d <= 7; ++d) if (d >= d0 && d <= d1) { const u32x4 z = *(const u32x4*)(ZP + (size_t)(row + d) * 512 + lane * 8);
;             acc[0] += bf_lo(z.x); acc[1] += bf_hi(z.x); acc[2] += bf_lo(z.y); acc[3] += bf_hi(z.y); acc[4] += bf_lo(z.z); acc[5] += bf_hi(z.z); acc[6] += bf_lo(z.w); acc[7] += bf_hi(z.w); }
	v_lshlrev_b32_e32 v20, 16, v162
	v_and_b32_e32 v21, 0xffff0000, v162
	v_lshlrev_b32_e32 v22, 16, v163
	v_and_b32_e32 v23, 0xffff0000, v163
	v_lshlrev_b32_e32 v24, 16, v164
	v_and_b32_e32 v25, 0xffff0000, v164
	v_lshlrev_b32_e32 v194, 16, v165
	v_and_b32_e32 v195, 0xffff0000, v165
	v_pk_add_f32 v[8:9], v[8:9], v[20:21]
	v_pk_add_f32 v[10:11], v[10:11], v[22:23]
	v_pk_add_f32 v[12:13], v[12:13], v[24:25]
	v_pk_add_f32 v[14:15], v[14:15], v[194:195]
	v_lshlrev_b32_e32 v20, 16, v166
	v_and_b32_e32 v21, 0xffff0000, v166
	v_lshlrev_b32_e32 v22, 16, v167
	v_and_b32_e32 v23, 0xffff0000, v167
	v_lshlrev_b32_e32 v24, 16, v168
	v_and_b32_e32 v25, 0xffff0000, v168
	v_lshlrev_b32_e32 v194, 16, v169
	v_and_b32_e32 v195, 0xffff0000, v169
	v_pk_add_f32 v[8:9], v[8:9], v[20:21]
	v_pk_add_f32 v[10:11], v[10:11], v[22:23]
	v_pk_add_f32 v[12:13], v[12:13], v[24:25]
	v_pk_add_f32 v[14:15], v[14:15], v[194:195]
	v_lshlrev_b32_e32 v20, 16, v170
	v_and_b32_e32 v21, 0xffff0000, v170
	v_lshlrev_b32_e32 v22, 16, v171
	v_and_b32_e32 v23, 0xffff0000, v171
	v_lshlrev_b32_e32 v24, 16, v172
	v_and_b32_e32 v25, 0xffff0000, v172
	v_lshlrev_b32_e32 v194, 16, v173
	v_and_b32_e32 v195, 0xffff0000, v173
	v_pk_add_f32 v[8:9], v[8:9], v[20:21]
	v_pk_add_f32 v[10:11], v[10:11], v[22:23]
	v_pk_add_f32 v[12:13], v[12:13], v[24:25]
	v_pk_add_f32 v[14:15], v[14:15], v[194:195]
	v_lshlrev_b32_e32 v20, 16, v174
	v_and_b32_e32 v21, 0xffff0000, v174
	v_lshlrev_b32_e32 v22, 16, v175
	v_and_b32_e32 v23, 0xffff0000, v175
	v_lshlrev_b32_e32 v24, 16, v176
	v_and_b32_e32 v25, 0xffff0000, v176
	v_lshlrev_b32_e32 v194, 16, v177
	v_and_b32_e32 v195, 0xffff0000, v177
	v_pk_add_f32 v[8:9], v[8:9], v[20:21]
	v_pk_add_f32 v[10:11], v[10:11], v[22:23]
	v_pk_add_f32 v[12:13], v[12:13], v[24:25]
	v_pk_add_f32 v[14:15], v[14:15], v[194:195]
	v_lshlrev_b32_e32 v20, 16, v178
	v_and_b32_e32 v21, 0xffff0000, v178
	v_lshlrev_b32_e32 v22, 16, v179
	v_and_b32_e32 v23, 0xffff0000, v179
	v_lshlrev_b32_e32 v24, 16, v180
	v_and_b32_e32 v25, 0xffff0000, v180
	v_lshlrev_b32_e32 v194, 16, v181
	v_and_b32_e32 v195, 0xffff0000, v181
	v_pk_add_f32 v[8:9], v[8:9], v[20:21]
	v_pk_add_f32 v[10:11], v[10:11], v[22:23]
	v_pk_add_f32 v[12:13], v[12:13], v[24:25]
	v_pk_add_f32 v[14:15], v[14:15], v[194:195]
	v_lshlrev_b32_e32 v20, 16, v182
	v_and_b32_e32 v21, 0xffff0000, v182
	v_lshlrev_b32_e32 v22, 16, v183
	v_and_b32_e32 v23, 0xffff0000, v183
	v_lshlrev_b32_e32 v24, 16, v184
	v_and_b32_e32 v25, 0xffff0000, v184
	v_lshlrev_b32_e32 v194, 16, v185
	v_and_b32_e32 v195, 0xffff0000, v185
	v_pk_add_f32 v[8:9], v[8:9], v[20:21]
	v_pk_add_f32 v[10:11], v[10:11], v[22:23]
	v_pk_add_f32 v[12:13], v[12:13], v[24:25]
	v_pk_add_f32 v[14:15], v[14:15], v[194:195]
	v_lshlrev_b32_e32 v20, 16, v186
	v_and_b32_e32 v21, 0xffff0000, v186
	v_lshlrev_b32_e32 v22, 16, v187
	v_and_b32_e32 v23, 0xffff0000, v187
	v_lshlrev_b32_e32 v24, 16, v188
	v_and_b32_e32 v25, 0xffff0000, v188
	v_lshlrev_b32_e32 v194, 16, v189
	v_and_b32_e32 v195, 0xffff0000, v189
	v_pk_add_f32 v[8:9], v[8:9], v[20:21]
	v_pk_add_f32 v[10:11], v[10:11], v[22:23]
	v_pk_add_f32 v[12:13], v[12:13], v[24:25]
	v_pk_add_f32 v[14:15], v[14:15], v[194:195]
	v_lshlrev_b32_e32 v20, 16, v190
	v_and_b32_e32 v21, 0xffff0000, v190
	v_lshlrev_b32_e32 v22, 16, v191
	v_and_b32_e32 v23, 0xffff0000, v191
	v_lshlrev_b32_e32 v24, 16, v192
	v_and_b32_e32 v25, 0xffff0000, v192
	v_lshlrev_b32_e32 v194, 16, v193
	v_and_b32_e32 v195, 0xffff0000, v193
	v_pk_add_f32 v[8:9], v[8:9], v[20:21]
	v_pk_add_f32 v[10:11], v[10:11], v[22:23]
	v_pk_add_f32 v[12:13], v[12:13], v[24:25]
	v_pk_add_f32 v[14:15], v[14:15], v[194:195]
	s_branch .LBB0_739
